# DA score tiles: 18 K-fragment LDS reads issued up to 14 deep with counted waits
# baseline (speedup 1.0000x reference)
; DI f32x4 mfma32(bf16x8 a, bf16x8 b, f32x4 c) { return __builtin_amdgcn_mfma_f32_16x16x32_bf16(a, b, c, 0, 0, 0); }
; #define DA_DECODE(UNIT) do { cfg = (UNIT) / 512; const int rem_ = (UNIT) % 512; h = rem_ >> 7; const int blk_ = rem_ & 127; d = 1 << (2 * cfg); L = Tg / d; const int nb128_ = L / 128, per_seq_ = d * nb128_; \
;         const int s_ = blk_ / per_seq_, r2_ = blk_ % per_seq_; rho = r2_ / nb128_; u0 = (r2_ % nb128_) * 128; seq0 = s_ * Tg; } while (0)
; DI void phase_da(const Ctx& c, LAS unsigned char* lds, int g, const bf16* PROJ, bf16* DAO, float* DALSE, int bid, int nb, int tid) {
;     ...
;         for (int tt = 0; tt < 9; ++tt) { f32x4 sv = {0.f, 0.f, 0.f, 0.f}; sv = mfma32(ld_contig(Kimg, 72, (w + tt) * 16, 0, lane), qf0, sv); sv = mfma32(ld_contig(Kimg, 72, (w + tt) * 16, 32, lane), qf1, sv); sc[tt] = sv; }
;         __builtin_amdgcn_sched_barrier(0);
;         const bool has_next = iu + wpx < UPX;
;         if (has_next) { DA_DECODE(xcd * UPX + iu + wpx); DA_LOAD(); }
.LBB0_238:
	s_and_b32 s1, s41, 1
	s_mul_i32 s8, s1, 0x122c0
	s_add_i32 s45, s8, 0
	v_add3_u32 v1, s45, v103, v136
	ds_read_b128 v[164:167], v1 offset:36864
	ds_read_b128 v[168:171], v1 offset:36928
	v_add3_u32 v1, s45, v105, v136
	ds_read_b128 v[172:175], v1 offset:36864
	ds_read_b128 v[176:179], v1 offset:36928
	v_add3_u32 v1, s45, v107, v136
	ds_read_b128 v[180:183], v1 offset:36864
	ds_read_b128 v[184:187], v1 offset:36928
	v_add3_u32 v1, s45, v109, v136
	ds_read_b128 v[188:191], v1 offset:36864
	ds_read_b128 v[192:195], v1 offset:36928
	v_add3_u32 v1, s45, v111, v136
	ds_read_b128 v[196:199], v1 offset:36864
	ds_read_b128 v[200:203], v1 offset:36928
	v_add3_u32 v1, s45, v113, v136
	ds_read_b128 v[204:207], v1 offset:36864
	ds_read_b128 v[208:211], v1 offset:36928
	v_add3_u32 v1, s45, v115, v136
	ds_read_b128 v[212:215], v1 offset:36864
	ds_read_b128 v[218:221], v1 offset:36928
	s_waitcnt vmcnt(5) lgkmcnt(13)
	v_mfma_f32_16x16x32_bf16 v[62:65], v[164:167], v[6:9], 0
	s_waitcnt vmcnt(4) lgkmcnt(12)
	v_mfma_f32_16x16x32_bf16 v[62:65], v[168:171], v[10:13], v[62:65]
	v_add3_u32 v1, s45, v117, v136
	ds_read_b128 v[222:225], v1 offset:36864
	ds_read_b128 v[226:229], v1 offset:36928
	s_waitcnt lgkmcnt(13)
	v_mfma_f32_16x16x32_bf16 v[78:81], v[172:175], v[6:9], 0
	s_waitcnt lgkmcnt(12)
	v_mfma_f32_16x16x32_bf16 v[78:81], v[176:179], v[10:13], v[78:81]
	v_add3_u32 v1, s45, v119, v136
	ds_read_b128 v[230:233], v1 offset:36864
	ds_read_b128 v[234:237], v1 offset:36928
	s_waitcnt lgkmcnt(13)
	v_mfma_f32_16x16x32_bf16 v[74:77], v[180:183], v[6:9], 0
	s_waitcnt lgkmcnt(12)
	v_mfma_f32_16x16x32_bf16 v[74:77], v[184:187], v[10:13], v[74:77]
	s_waitcnt lgkmcnt(11)
	v_mfma_f32_16x16x32_bf16 v[70:73], v[188:191], v[6:9], 0
	s_waitcnt lgkmcnt(10)
	v_mfma_f32_16x16x32_bf16 v[70:73], v[192:195], v[10:13], v[70:73]
	s_waitcnt lgkmcnt(9)
	v_mfma_f32_16x16x32_bf16 v[66:69], v[196:199], v[6:9], 0
	s_waitcnt lgkmcnt(8)
	v_mfma_f32_16x16x32_bf16 v[66:69], v[200:203], v[10:13], v[66:69]
	s_waitcnt lgkmcnt(7)
	v_mfma_f32_16x16x32_bf16 v[58:61], v[204:207], v[6:9], 0
	s_waitcnt lgkmcnt(6)
	v_mfma_f32_16x16x32_bf16 v[58:61], v[208:211], v[10:13], v[58:61]
	s_waitcnt lgkmcnt(5)
	v_mfma_f32_16x16x32_bf16 v[50:53], v[212:215], v[6:9], 0
	s_waitcnt lgkmcnt(4)
	v_mfma_f32_16x16x32_bf16 v[50:53], v[218:221], v[10:13], v[50:53]
	s_waitcnt lgkmcnt(3)
	v_mfma_f32_16x16x32_bf16 v[54:57], v[222:225], v[6:9], 0
	s_waitcnt lgkmcnt(2)
	v_mfma_f32_16x16x32_bf16 v[54:57], v[226:229], v[10:13], v[54:57]
	s_waitcnt lgkmcnt(1)
	v_mfma_f32_16x16x32_bf16 v[46:49], v[230:233], v[6:9], 0
	s_waitcnt lgkmcnt(0)
	v_mfma_f32_16x16x32_bf16 v[46:49], v[234:237], v[10:13], v[46:49]
	s_cmp_lt_i32 s42, s38
	s_cselect_b64 s[14:15], -1, 0
	s_cmp_ge_i32 s42, s38
	s_cbranch_scc1 .LBB0_252
	s_add_i32 s8, s39, s42
	s_ashr_i32 s9, s8, 31
	s_lshr_b32 s9, s9, 23
	s_add_i32 s9, s8, s9
	s_ashr_i32 s18, s9, 9
	s_lshl_b32 s47, s18, 1
	s_lshr_b32 s19, s57, s47
	s_lshr_b32 s35, s19, 7
	s_lshl_b32 s34, s35, s47
	s_abs_i32 s36, s34
	v_cvt_f32_u32_e32 v1, s36
	s_sub_i32 s37, 0, s36
	s_and_b32 s9, s9, 0xfffffe00
	s_sub_i32 s8, s8, s9
	v_rcp_iflag_f32_e32 v1, v1
	s_ashr_i32 s34, s8, 7
	v_mov_b32_e32 v245, 0x81
	v_mad_i64_i32 v[246:247], vcc, s18, v245, v[84:85]
	s_and_b64 s[100:101], s[2:3], s[4:5]
	s_and_saveexec_b64 s[98:99], s[100:101]
	global_load_ubyte v244, v[246:247], off offset:-16
	s_mov_b64 exec, s[98:99]
	s_and_b32 s8, s8, 0x7f
	s_lshr_b32 s9, s8, s58
	v_mul_f32_e32 v1, 0x4f7ffffe, v1
	v_cvt_u32_f32_e32 v1, v1
	v_mov_b32_e32 v89, v0
	v_mov_b32_e32 v16, v0
	v_mov_b32_e32 v17, v0
	v_readfirstlane_b32 s43, v1
	s_mul_i32 s37, s37, s43
	s_mul_hi_u32 s37, s43, s37
	s_add_i32 s43, s43, s37
	s_mul_hi_u32 s37, s8, s43
	s_mul_i32 s37, s37, s36
	s_sub_i32 s8, s8, s37
	s_sub_i32 s37, s8, s36
	s_cmp_ge_u32 s8, s36
	s_cselect_b32 s8, s37, s8
	s_sub_i32 s37, s8, s36
	s_cmp_ge_u32 s8, s36
	s_cselect_b32 s8, s37, s8
	s_sub_i32 s36, s50, s47
	s_add_i32 s37, s35, -1
	s_lshr_b32 s35, s8, s36
	s_and_b32 s8, s8, s37
	s_lshl_b32 s43, s8, 7
	s_lshl_b32 s44, s9, s59
	v_add_u32_e32 v1, s43, v98
	v_lshlrev_b32_e32 v1, s47, v1
	s_or_b32 s36, s35, s44
	v_add_u32_e32 v2, s36, v1
	v_ashrrev_i32_e32 v3, 31, v2
	s_lshl_b32 s8, s34, 6
	v_lshlrev_b64 v[2:3], 13, v[2:3]
	s_ashr_i32 s9, s8, 31
	v_lshl_add_u64 v[2:3], s[82:83], 0, v[2:3]
	s_lshl_b64 s[8:9], s[8:9], 1
	v_lshl_add_u64 v[2:3], v[2:3], 0, s[8:9]
	v_lshl_add_u64 v[2:3], v[2:3], 0, v[88:89]
	s_and_saveexec_b64 s[98:99], s[2:3]
	s_cbranch_execz .Lda_t5_done
	v_mov_b32_e32 v96, 0xf149f2ca
	s_and_b64 exec, exec, s[4:5]
	s_waitcnt vmcnt(0)
	v_lshl_add_u32 v248, v244, 2, s34
	v_ashrrev_i32_e32 v249, 31, v248
	v_lshl_add_u64 v[248:249], v[248:249], 2, s[66:67]
	global_load_dword v96, v[248:249], off
